# select: arrival-order tile shares made steeper (first three waves every 4th tile, next two every 8th, last three none)
# speedup vs baseline: 1.0078x; 1.0008x over previous
; #define KI_LOAD(dst, i0) do { _Pragma("unroll") for (int t_ = 0; t_ < 2; ++t_) { int kt_ = ktlo + wave + 8 * ((i0) + t_); kt_ = kt_ < kthi ? kt_ : kthi - 1; \
;                 dst[t_][0] = *(const bf16x8*)(kib + (size_t)kt_ * 1024); dst[t_][1] = *(const bf16x8*)(kib + (size_t)kt_ * 1024 + 512); } } while (0)
; __device__ __forceinline__ void select_phase(const bf16_t* Z, const bf16_t* KIb, unsigned* MASKb, unsigned* itemcnt, LAS unsigned char* lds, int wave_in, int lane_in, int bid, int G, int sub) {
;     ...
;                 const int ktlo = 128 * c, kthi = min(nkt, ktlo + 128);
;                 bf16x8 ka[2][2], kb2[2][2];
;     ...
;                 KI_LOAD(ka, 0);
;                 for (int i0 = 0; ktlo + wave + 8 * i0 < kthi; i0 += 4) { KI_LOAD(kb2, i0 + 2); KI_COMP(ka, i0); KI_LOAD(ka, i0 + 4); KI_COMP(kb2, i0 + 2); }
.Lsf_cont:
	v_lshlrev_b32_e32 v72, 16, v70
	v_and_b32_e32 v74, 0xffff0000, v70
	v_lshlrev_b32_e32 v76, 16, v71
	v_and_b32_e32 v78, 0xffff0000, v71
	v_mov_b32_e32 v106, s75
	v_and_b32_e32 v171, -16, v68
	v_mul_lo_u32 v0, v68, s4
	s_cmp_lt_i32 s10, 1
	v_lshlrev_b32_e32 v172, 5, v68
	s_cbranch_scc1 .LBB0_128
	s_cmp_lt_i32 s100, 0
	s_cbranch_scc1 .Lrk_even
	v_mov_b32_e32 v208, 0x24440
	v_mov_b32_e32 v209, 1
	s_mov_b64 vcc, exec
	s_mov_b64 exec, 1
	ds_add_rtn_u32 v208, v208, v209
	s_mov_b64 exec, vcc
	s_waitcnt lgkmcnt(0)
	v_readfirstlane_b32 s26, v208
	s_and_b32 s26, s26, 7
	s_lshl_b32 s27, s26, 2
	s_add_i32 s28, s27, -9
	s_movk_i32 s29, 0x7fff
	s_cmp_lt_u32 s26, 5
	s_cselect_b32 s29, s28, s29
	s_cselect_b32 s27, 8, 16
	s_cmp_lt_u32 s26, 3
	s_cselect_b32 s29, s26, s29
	s_cselect_b32 s27, 4, s27
	s_branch .Lrk_set
